# SSM phase: one static s_setprio 1 for the latent-scan waves (0-3), reset at the end of the phase
# speedup vs baseline: 1.0020x; 1.0020x over previous
.LBB0_340:
	s_cmp_lt_i32 s96, 4
	s_cselect_b64 s[0:1], -1, 0
	s_and_b64 s[8:9], s[0:1], s[4:5]
	s_andn2_b64 vcc, exec, s[8:9]
	s_cbranch_vccnz .LBB0_393
	v_cmp_gt_u32_e32 vcc, 2, v190
	s_and_saveexec_b64 s[0:1], vcc
	v_lshlrev_b32_e32 v2, 2, v190
	v_add_u32_e32 v2, 0x21000, v2
	v_mov_b32_e32 v3, 0
	ds_write_b32 v2, v3
	s_mov_b64 exec, s[0:1]
	v_and_b32_e32 v172, 31, v191
	v_lshrrev_b32_e32 v173, 5, v191
	v_and_b32_e32 v174, 1, v191
	v_and_b32_e32 v175, 15, v191
	v_lshrrev_b32_e32 v176, 4, v191
	s_mul_i32 s20, s89, 0x3200
	v_lshl_add_u32 v151, v191, 2, s20
	v_mul_u32_u24_e32 v182, 0x110, v175
	v_lshl_add_u32 v182, v176, 4, v182
	v_add_u32_e32 v152, s20, v182
	v_lshlrev_b32_e32 v182, 5, v172
	v_lshl_add_u32 v150, v173, 4, v182
	v_xor_b32_e32 v193, 0x80, v150
	s_mov_b32 s66, 0x0f0f0f0f
	s_mov_b32 s67, 0x0f0f0f0f
	s_mov_b32 s68, 0xf0f0f0f0
	s_mov_b32 s69, 0xf0f0f0f0
	v_lshlrev_b32_e32 v182, 5, v172
	v_lshl_add_u32 v182, v173, 4, v182
	s_add_u32 s22, s20, 0x2200
	v_add_u32_e32 v162, s22, v182
	v_lshlrev_b32_e32 v182, 5, v175
	v_lshl_add_u32 v182, v176, 3, v182
	v_add_u32_e32 v163, s22, v182
	v_mul_u32_u24_e32 v182, 0x1800, v175
	v_lshl_add_u32 v154, v176, 3, v182
	v_add_u32_e32 v158, 0x18000, v154
	v_lshlrev_b32_e32 v182, 12, v175
	v_lshlrev_b32_e32 v182, 6, v175
	v_lshl_add_u32 v153, v176, 4, v182
	v_add_u32_e32 v157, 0x400, v153
	v_lshlrev_b32_e32 v182, 11, v175
	v_lshl_add_u32 v156, v176, 3, v182
	v_add_u32_e32 v159, 0x8000, v156
	s_and_b32 s21, s89, 3
	s_lshl_b32 s21, s21, 13
	s_add_u32 s21, s21, 0x19000
	v_lshlrev_b32_e32 v182, 5, v175
	v_lshl_add_u32 v182, v176, 3, v182
	v_add_u32_e32 v155, s21, v182
	v_lshrrev_b32_e32 v182, 3, v172
	v_lshlrev_b32_e32 v182, 10, v182
	v_and_b32_e32 v183, 7, v172
	v_lshl_add_u32 v182, v183, 5, v182
	v_lshl_add_u32 v177, v173, 8, v182
	v_lshlrev_b32_e32 v178, 4, v191
	v_lshlrev_b32_e32 v179, 3, v191
	v_lshlrev_b32_e32 v180, 2, v191
	v_add_u32_e32 v170, 0x4000, v180
	v_lshlrev_b32_e32 v181, 4, v176
	v_mov_b32_e32 v1, 0x3dd2d3e8
	s_waitcnt vmcnt(0) lgkmcnt(0)
	s_barrier
	s_cmp_lt_u32 s89, 4
	s_cbranch_scc0 .Lssm_ctx
	s_setprio 1
	s_lshr_b32 s21, s89, 1
	s_and_b32 s22, s2, 7
	s_lshl_b32 s22, s22, 6
	s_lshr_b32 s26, s2, 3
	s_lshl_b32 s26, s26, 1
	s_add_u32 s22, s22, s26
	s_add_u32 s22, s22, s21
	s_lshr_b32 s23, s22, 6
	s_and_b32 s24, s22, 63
	s_lshl_b32 s25, s23, 10
	s_add_u32 s25, s25, 0x2000
	s_and_b32 s26, s89, 1
	s_cmp_eq_u32 s26, 0
	s_cbranch_scc0 .Lssm_lat_bwd
	s_add_u32 s28, s24, 0
	s_lshl_b32 s29, s28, 13
	s_add_u32 s29, s29, 0x200000
	s_add_u32 s10, s62, s29
	s_addc_u32 s11, s63, 0
	global_load_dwordx4 v[84:87], v177, s[10:11]
	global_load_dwordx4 v[88:91], v177, s[10:11] offset:16
	s_add_u32 s12, s10, 0x1000
	s_addc_u32 s13, s11, 0
	global_load_dwordx4 v[92:95], v177, s[12:13]
	global_load_dwordx4 v[96:99], v177, s[12:13] offset:16
	s_lshl_b32 s29, s28, 12
	s_add_u32 s29, s29, 0x300000
	s_add_u32 s16, s62, s29
	s_addc_u32 s17, s63, 0
	global_load_dwordx4 v[100:103], v178, s[16:17]
	global_load_dwordx4 v[104:107], v178, s[16:17] offset:1024
	global_load_dwordx4 v[108:111], v178, s[16:17] offset:2048
	global_load_dwordx4 v[112:115], v178, s[16:17] offset:3072
	s_lshl_b32 s29, s28, 9
	s_add_u32 s29, s29, 0x100000
	s_add_u32 s18, s62, s29
	s_addc_u32 s19, s63, 0
	global_load_dwordx2 v[116:117], v179, s[18:19]
	s_lshl_b32 s30, s23, 1
	s_lshl_b32 s30, s30, 15
	s_lshl_b32 s31, s24, 8
	s_add_u32 s30, s30, s31
	v_readlane_b32 s34, v254, 10
	v_readlane_b32 s35, v254, 11
	s_nop 3
	s_add_u32 s34, s34, s30
	s_addc_u32 s35, s35, 0
	global_load_dword v120, v180, s[34:35]
	global_load_dword v121, v170, s[34:35]
	v_readlane_b32 s34, v254, 28
	v_readlane_b32 s35, v254, 29
	s_nop 3
	s_lshl_b32 s31, s24, 6
	s_add_u32 s34, s34, s31
	s_addc_u32 s35, s35, 0
	global_load_dwordx4 v[164:167], v181, s[34:35]
	s_lshl_b32 s31, s25, 5
	s_lshl_b32 s29, s24, 19
	s_add_u32 s31, s31, s29
	s_add_u32 s31, s31, 0x16800000
	s_add_u32 s4, s62, s31
	s_addc_u32 s5, s63, 0
	s_lshl_b32 s31, s22, 1
	s_lshl_b32 s31, s31, 15
	s_add_u32 s31, s31, 0x4800000
	s_add_u32 s6, s62, s31
	s_addc_u32 s7, s63, 0
	s_add_u32 s34, s4, 0
	s_addc_u32 s35, s5, 0
	global_load_dwordx4 v[80:83], v150, s[34:35]
	global_load_dwordx4 v[194:197], v193, s[34:35]
	s_mov_b64 s[10:11], s[34:35]
	s_add_u32 s10, s10, 1024
	s_addc_u32 s11, s11, 0
	global_load_dwordx4 v[144:147], v150, s[10:11]
	global_load_dwordx4 v[168:171], v193, s[10:11]
	s_mov_b64 s[34:35], s[10:11]
	s_add_u32 s10, s10, 1024
	s_addc_u32 s11, s11, 0
	s_add_u32 s12, s6, 0
	s_addc_u32 s13, s7, 0
	s_mov_b32 s14, 0
	s_mov_b32 s40, 0xffff0000
	s_waitcnt vmcnt(0)
	v_xor_b32_e32 v118, 0x80000000, v117

.Lssm_done:
	s_setprio 0
	s_waitcnt vmcnt(0) lgkmcnt(0)
	s_barrier
	s_mov_b64 s[4:5], exec
	v_readlane_b32 s6, v254, 2
	v_readlane_b32 s7, v254, 3
	s_nop 1
	s_and_b64 s[6:7], s[4:5], s[6:7]
	s_mov_b64 exec, s[6:7]
	s_cbranch_execz .Lp3_arrive_join
	s_getreg_b32 s10, hwreg(HW_REG_XCC_ID, 0, 4)
	v_mov_b32_e32 v2, 0x23fc0
	ds_read_b64 v[2:3], v2
	s_lshl_b32 s10, s10, 6
	s_add_u32 s12, s62, 0x40e000
	s_addc_u32 s13, s63, 0
	v_mov_b32_e32 v4, s10
	v_mov_b32_e32 v5, 1
	global_atomic_add v6, v4, v5, s[12:13] sc0
	s_waitcnt vmcnt(0) lgkmcnt(0)
	v_add_u32_e32 v6, 1, v6
	v_cmp_eq_u32_e32 vcc, v6, v2
	s_cbranch_vccz .Lp3_arrive_join
	buffer_wbl2 sc1
	s_waitcnt vmcnt(0)
	v_mov_b32_e32 v4, 0x400
	global_atomic_add v4, v5, s[12:13]
